# adds: gates_phase loads batched (32 up front per row pair instead of load-wait x32), scan_phase loads hoisted with incremental addresses
# speedup vs baseline: 1.0278x; 1.0278x over previous
; __device__ __forceinline__ int opaque_tid() { int t = threadIdx.x; asm volatile("" : "+v"(t)); return t; }
; DI void scan_phase(float* STATE, const float* SC, int G, int bid) {
;     ...
;     for (int el = bid * 512 + opaque_tid(); el < total; el += G * 512) {
;         const int bh = el / ST_STRIDE, e = el % ST_STRIDE; float cur = 0.f, mcur = 0.f;
; #pragma unroll
;         for (int s2 = 0; s2 < 16; ++s2) { const int uid = bh * 16 + s2; float* p = STATE + (size_t)uid * ST_STRIDE + e; const float l = *p; *p = cur;
;             const float ml = SC[uid * 2], gsg = SC[uid * 2 + 1]; const float mo = fmaxf(gsg + mcur, ml);
;             cur = __expf(gsg + mcur - mo) * cur + __expf(ml - mo) * l; mcur = mo; }
;     }
.LBB0_176:
	s_mov_b32 s2, 0x7f807f81
	v_mul_hi_i32 v0, v2, s2
	v_lshrrev_b32_e32 v1, 31, v0
	v_ashrrev_i32_e32 v0, 14, v0
	v_add_u32_e32 v6, v0, v1
	v_mul_i32_i24_e32 v0, 0x8080, v6
	v_sub_u32_e32 v0, v2, v0
	v_lshlrev_b32_e32 v3, 4, v6
	v_ashrrev_i32_e32 v1, 31, v0
	v_lshl_add_u64 v[0:1], v[0:1], 2, s[94:95]
	v_mul_hi_i32_i24_e32 v5, 0x20200, v3
	v_mul_i32_i24_e32 v4, 0x20200, v3
	v_lshl_add_u64 v[10:11], v[0:1], 0, v[4:5]
	v_lshlrev_b32_e32 v4, 5, v6
	v_ashrrev_i32_e32 v5, 31, v4
	v_lshl_add_u64 v[90:91], v[4:5], 2, s[22:23]
	v_mov_b32_e32 v92, 0x20200
	v_mov_b32_e32 v93, 0
	v_lshl_add_u64 v[12:13], v[10:11], 0, v[92:93]
	v_lshl_add_u64 v[14:15], v[12:13], 0, v[92:93]
	v_lshl_add_u64 v[16:17], v[14:15], 0, v[92:93]
	v_lshl_add_u64 v[18:19], v[16:17], 0, v[92:93]
	v_lshl_add_u64 v[20:21], v[18:19], 0, v[92:93]
	v_lshl_add_u64 v[22:23], v[20:21], 0, v[92:93]
	v_lshl_add_u64 v[24:25], v[22:23], 0, v[92:93]
	v_lshl_add_u64 v[26:27], v[24:25], 0, v[92:93]
	v_lshl_add_u64 v[28:29], v[26:27], 0, v[92:93]
	v_lshl_add_u64 v[30:31], v[28:29], 0, v[92:93]
	v_lshl_add_u64 v[32:33], v[30:31], 0, v[92:93]
	v_lshl_add_u64 v[34:35], v[32:33], 0, v[92:93]
	v_lshl_add_u64 v[36:37], v[34:35], 0, v[92:93]
	v_lshl_add_u64 v[38:39], v[36:37], 0, v[92:93]
	v_lshl_add_u64 v[40:41], v[38:39], 0, v[92:93]
	global_load_dword v42, v[10:11], off
	global_load_dword v43, v[12:13], off
	global_load_dword v44, v[14:15], off
	global_load_dword v45, v[16:17], off
	global_load_dword v46, v[18:19], off
	global_load_dword v47, v[20:21], off
	global_load_dword v48, v[22:23], off
	global_load_dword v49, v[24:25], off
	global_load_dword v50, v[26:27], off
	global_load_dword v51, v[28:29], off
	global_load_dword v52, v[30:31], off
	global_load_dword v53, v[32:33], off
	global_load_dword v54, v[34:35], off
	global_load_dword v55, v[36:37], off
	global_load_dword v56, v[38:39], off
	global_load_dwordx2 v[58:59], v[90:91], off
	global_load_dwordx2 v[60:61], v[90:91], off offset:8
	global_load_dwordx2 v[62:63], v[90:91], off offset:16
	global_load_dwordx2 v[64:65], v[90:91], off offset:24
	global_load_dwordx2 v[66:67], v[90:91], off offset:32
	global_load_dwordx2 v[68:69], v[90:91], off offset:40
	global_load_dwordx2 v[70:71], v[90:91], off offset:48
	global_load_dwordx2 v[72:73], v[90:91], off offset:56
	global_load_dwordx2 v[74:75], v[90:91], off offset:64
	global_load_dwordx2 v[76:77], v[90:91], off offset:72
	global_load_dwordx2 v[78:79], v[90:91], off offset:80
	global_load_dwordx2 v[80:81], v[90:91], off offset:88
	global_load_dwordx2 v[82:83], v[90:91], off offset:96
	global_load_dwordx2 v[84:85], v[90:91], off offset:104
	global_load_dwordx2 v[86:87], v[90:91], off offset:112
	v_add_u32_e32 v2, s96, v2
	s_mov_b32 s2, 0x807ff
	v_cmp_lt_i32_e32 vcc, s2, v2
	s_or_b64 s[38:39], vcc, s[38:39]
	global_store_dword v[10:11], v113, off
	s_waitcnt vmcnt(15)
	v_add_f32_e32 v5, 0, v59
	v_max_f32_e32 v6, v58, v58
	v_max_f32_e32 v6, v5, v6
	v_sub_f32_e32 v4, v58, v6
	v_sub_f32_e32 v5, v5, v6
	v_mul_f32_e32 v4, 0x3fb8aa3b, v4
	v_mul_f32_e32 v5, 0x3fb8aa3b, v5
	v_exp_f32_e32 v4, v4
	v_exp_f32_e32 v5, v5
	v_mul_f32_e32 v8, v42, v4
	v_fmac_f32_e32 v8, 0, v5
	global_store_dword v[12:13], v8, off
	s_waitcnt vmcnt(15)
	v_add_f32_e32 v5, v6, v61
	v_max_f32_e32 v6, v60, v60
	v_max_f32_e32 v6, v5, v6
	v_sub_f32_e32 v4, v60, v6
	v_sub_f32_e32 v5, v5, v6
	v_mul_f32_e32 v4, 0x3fb8aa3b, v4
	v_mul_f32_e32 v5, 0x3fb8aa3b, v5
	v_exp_f32_e32 v4, v4
	v_exp_f32_e32 v5, v5
	v_mul_f32_e32 v7, v43, v4
	v_fmac_f32_e32 v7, v8, v5
	global_store_dword v[14:15], v7, off
	s_waitcnt vmcnt(15)
	v_add_f32_e32 v5, v6, v63
	v_max_f32_e32 v6, v62, v62
	v_max_f32_e32 v6, v5, v6
	v_sub_f32_e32 v4, v62, v6
	v_sub_f32_e32 v5, v5, v6
	v_mul_f32_e32 v4, 0x3fb8aa3b, v4
	v_mul_f32_e32 v5, 0x3fb8aa3b, v5
	v_exp_f32_e32 v4, v4
	v_exp_f32_e32 v5, v5
	v_mul_f32_e32 v8, v44, v4
	v_fmac_f32_e32 v8, v7, v5
	global_store_dword v[16:17], v8, off
	s_waitcnt vmcnt(15)
	v_add_f32_e32 v5, v6, v65
	v_max_f32_e32 v6, v64, v64
	v_max_f32_e32 v6, v5, v6
	v_sub_f32_e32 v4, v64, v6
	v_sub_f32_e32 v5, v5, v6
	v_mul_f32_e32 v4, 0x3fb8aa3b, v4
	v_mul_f32_e32 v5, 0x3fb8aa3b, v5
	v_exp_f32_e32 v4, v4
	v_exp_f32_e32 v5, v5
	v_mul_f32_e32 v7, v45, v4
	v_fmac_f32_e32 v7, v8, v5
	global_store_dword v[18:19], v7, off
	s_waitcnt vmcnt(15)
; DI void scan_phase(float* STATE, const float* SC, int G, int bid) {
;     ...
;         for (int s2 = 0; s2 < 16; ++s2) { const int uid = bh * 16 + s2; float* p = STATE + (size_t)uid * ST_STRIDE + e; const float l = *p; *p = cur;
;             const float ml = SC[uid * 2], gsg = SC[uid * 2 + 1]; const float mo = fmaxf(gsg + mcur, ml);
;             cur = __expf(gsg + mcur - mo) * cur + __expf(ml - mo) * l; mcur = mo; }
;     }
	v_add_f32_e32 v5, v6, v67
	v_max_f32_e32 v6, v66, v66
	v_max_f32_e32 v6, v5, v6
	v_sub_f32_e32 v4, v66, v6
	v_sub_f32_e32 v5, v5, v6
	v_mul_f32_e32 v4, 0x3fb8aa3b, v4
	v_mul_f32_e32 v5, 0x3fb8aa3b, v5
	v_exp_f32_e32 v4, v4
	v_exp_f32_e32 v5, v5
	v_mul_f32_e32 v8, v46, v4
	v_fmac_f32_e32 v8, v7, v5
	global_store_dword v[20:21], v8, off
	s_waitcnt vmcnt(15)
	v_add_f32_e32 v5, v6, v69
	v_max_f32_e32 v6, v68, v68
	v_max_f32_e32 v6, v5, v6
	v_sub_f32_e32 v4, v68, v6
	v_sub_f32_e32 v5, v5, v6
	v_mul_f32_e32 v4, 0x3fb8aa3b, v4
	v_mul_f32_e32 v5, 0x3fb8aa3b, v5
	v_exp_f32_e32 v4, v4
	v_exp_f32_e32 v5, v5
	v_mul_f32_e32 v7, v47, v4
	v_fmac_f32_e32 v7, v8, v5
	global_store_dword v[22:23], v7, off
	s_waitcnt vmcnt(15)
	v_add_f32_e32 v5, v6, v71
	v_max_f32_e32 v6, v70, v70
	v_max_f32_e32 v6, v5, v6
	v_sub_f32_e32 v4, v70, v6
	v_sub_f32_e32 v5, v5, v6
	v_mul_f32_e32 v4, 0x3fb8aa3b, v4
	v_mul_f32_e32 v5, 0x3fb8aa3b, v5
	v_exp_f32_e32 v4, v4
	v_exp_f32_e32 v5, v5
	v_mul_f32_e32 v8, v48, v4
	v_fmac_f32_e32 v8, v7, v5
	global_store_dword v[24:25], v8, off
	s_waitcnt vmcnt(15)
	v_add_f32_e32 v5, v6, v73
	v_max_f32_e32 v6, v72, v72
	v_max_f32_e32 v6, v5, v6
	v_sub_f32_e32 v4, v72, v6
	v_sub_f32_e32 v5, v5, v6
	v_mul_f32_e32 v4, 0x3fb8aa3b, v4
	v_mul_f32_e32 v5, 0x3fb8aa3b, v5
	v_exp_f32_e32 v4, v4
	v_exp_f32_e32 v5, v5
	v_mul_f32_e32 v7, v49, v4
	v_fmac_f32_e32 v7, v8, v5
	global_store_dword v[26:27], v7, off
	s_waitcnt vmcnt(15)
	v_add_f32_e32 v5, v6, v75
	v_max_f32_e32 v6, v74, v74
	v_max_f32_e32 v6, v5, v6
	v_sub_f32_e32 v4, v74, v6
	v_sub_f32_e32 v5, v5, v6
	v_mul_f32_e32 v4, 0x3fb8aa3b, v4
	v_mul_f32_e32 v5, 0x3fb8aa3b, v5
	v_exp_f32_e32 v4, v4
	v_exp_f32_e32 v5, v5
	v_mul_f32_e32 v8, v50, v4
	v_fmac_f32_e32 v8, v7, v5
	global_store_dword v[28:29], v8, off
	s_waitcnt vmcnt(15)
	v_add_f32_e32 v5, v6, v77
	v_max_f32_e32 v6, v76, v76
	v_max_f32_e32 v6, v5, v6
	v_sub_f32_e32 v4, v76, v6
	v_sub_f32_e32 v5, v5, v6
	v_mul_f32_e32 v4, 0x3fb8aa3b, v4
	v_mul_f32_e32 v5, 0x3fb8aa3b, v5
	v_exp_f32_e32 v4, v4
	v_exp_f32_e32 v5, v5
	v_mul_f32_e32 v7, v51, v4
	v_fmac_f32_e32 v7, v8, v5
	global_store_dword v[30:31], v7, off
	s_waitcnt vmcnt(15)
	v_add_f32_e32 v5, v6, v79
	v_max_f32_e32 v6, v78, v78
	v_max_f32_e32 v6, v5, v6
	v_sub_f32_e32 v4, v78, v6
	v_sub_f32_e32 v5, v5, v6
	v_mul_f32_e32 v4, 0x3fb8aa3b, v4
	v_mul_f32_e32 v5, 0x3fb8aa3b, v5
	v_exp_f32_e32 v4, v4
	v_exp_f32_e32 v5, v5
	v_mul_f32_e32 v8, v52, v4
	v_fmac_f32_e32 v8, v7, v5
	global_store_dword v[32:33], v8, off
	s_waitcnt vmcnt(15)
	v_add_f32_e32 v5, v6, v81
	v_max_f32_e32 v6, v80, v80
	v_max_f32_e32 v6, v5, v6
	v_sub_f32_e32 v4, v80, v6
	v_sub_f32_e32 v5, v5, v6
	v_mul_f32_e32 v4, 0x3fb8aa3b, v4
	v_mul_f32_e32 v5, 0x3fb8aa3b, v5
	v_exp_f32_e32 v4, v4
	v_exp_f32_e32 v5, v5
	v_mul_f32_e32 v7, v53, v4
	v_fmac_f32_e32 v7, v8, v5
	global_store_dword v[34:35], v7, off
	s_waitcnt vmcnt(15)
	v_add_f32_e32 v5, v6, v83
	v_max_f32_e32 v6, v82, v82
	v_max_f32_e32 v6, v5, v6
	v_sub_f32_e32 v4, v82, v6
	v_sub_f32_e32 v5, v5, v6
	v_mul_f32_e32 v4, 0x3fb8aa3b, v4
	v_mul_f32_e32 v5, 0x3fb8aa3b, v5
	v_exp_f32_e32 v4, v4
	v_exp_f32_e32 v5, v5
	v_mul_f32_e32 v8, v54, v4
	v_fmac_f32_e32 v8, v7, v5
	global_store_dword v[36:37], v8, off
	s_waitcnt vmcnt(15)
	v_add_f32_e32 v5, v6, v85
	v_max_f32_e32 v6, v84, v84
	v_max_f32_e32 v6, v5, v6
	v_sub_f32_e32 v4, v84, v6
	v_sub_f32_e32 v5, v5, v6
	v_mul_f32_e32 v4, 0x3fb8aa3b, v4
	v_mul_f32_e32 v5, 0x3fb8aa3b, v5
	v_exp_f32_e32 v4, v4
	v_exp_f32_e32 v5, v5
	v_mul_f32_e32 v7, v55, v4
	v_fmac_f32_e32 v7, v8, v5
	global_store_dword v[38:39], v7, off
	s_waitcnt vmcnt(15)
	v_add_f32_e32 v5, v6, v87
	v_max_f32_e32 v6, v86, v86
	v_max_f32_e32 v6, v5, v6
	v_sub_f32_e32 v4, v86, v6
	v_sub_f32_e32 v5, v5, v6
	v_mul_f32_e32 v4, 0x3fb8aa3b, v4
	v_mul_f32_e32 v5, 0x3fb8aa3b, v5
	v_exp_f32_e32 v4, v4
	v_exp_f32_e32 v5, v5
	v_mul_f32_e32 v8, v56, v4
	v_fmac_f32_e32 v8, v7, v5
	global_store_dword v[40:41], v8, off
	s_andn2_b64 exec, exec, s[38:39]
	s_cbranch_execnz .LBB0_176

; #define LAS __attribute__((address_space(3)))
; DI void gates_phase(LAS unsigned char* lds, const bf16_t* X, const ss_t* ss, const float* win  , const float* ng, const float* gbias, float* GATES, int G, int bid) {
;     ...
;         const bf16_t* xr0 = X + (size_t)m0 * 1024; const bf16_t* xr1 = X + (size_t)(m0 + NGW) * 1024;
; #pragma unroll 4
;         for (int i = 0; i < 16; ++i) { const int k = lane + 64 * i; const float x0 = __builtin_bit_cast(float, (unsigned)xr0[k] << 16), x1 = __builtin_bit_cast(float, (unsigned)xr1[k] << 16); const f32x4 a = *(const LAS f32x4*)(wg + k * 8), b = *(const LAS f32x4*)(wg + k * 8 + 4);
; #pragma unroll
;             for (int e = 0; e < 4; ++e) { acc[0][e] += x0 * a[e]; acc[0][4 + e] += x0 * b[e]; acc[1][e] += x1 * a[e]; acc[1][4 + e] += x1 * b[e]; } }
.LBB0_446:
	global_load_ushort v52, v[8:9], off offset:-256
	global_load_ushort v53, v[6:7], off offset:-256
	global_load_ushort v54, v[8:9], off offset:-128
	global_load_ushort v55, v[6:7], off offset:-128
	global_load_ushort v56, v[8:9], off
	global_load_ushort v57, v[6:7], off
	global_load_ushort v58, v[8:9], off offset:128
	global_load_ushort v59, v[6:7], off offset:128
	global_load_ushort v60, v[8:9], off offset:256
	global_load_ushort v61, v[6:7], off offset:256
	global_load_ushort v62, v[8:9], off offset:384
	global_load_ushort v63, v[6:7], off offset:384
	global_load_ushort v64, v[8:9], off offset:512
	global_load_ushort v65, v[6:7], off offset:512
	global_load_ushort v66, v[8:9], off offset:640
	global_load_ushort v67, v[6:7], off offset:640
	global_load_ushort v68, v[8:9], off offset:768
	global_load_ushort v69, v[6:7], off offset:768
	global_load_ushort v70, v[8:9], off offset:896
	global_load_ushort v71, v[6:7], off offset:896
	global_load_ushort v72, v[8:9], off offset:1024
	global_load_ushort v73, v[6:7], off offset:1024
	global_load_ushort v74, v[8:9], off offset:1152
	global_load_ushort v75, v[6:7], off offset:1152
	global_load_ushort v76, v[8:9], off offset:1280
	global_load_ushort v77, v[6:7], off offset:1280
	global_load_ushort v78, v[8:9], off offset:1408
	global_load_ushort v79, v[6:7], off offset:1408
	global_load_ushort v80, v[8:9], off offset:1536
	global_load_ushort v81, v[6:7], off offset:1536
	global_load_ushort v82, v[8:9], off offset:1664
	global_load_ushort v83, v[6:7], off offset:1664
	s_waitcnt vmcnt(31)
	v_lshlrev_b32_e32 v44, 16, v52
	ds_read_b128 v[34:37], v1
	ds_read_b128 v[38:41], v1 offset:16
	s_waitcnt lgkmcnt(1)
	v_pk_fma_f32 v[18:19], v[36:37], v[44:45], v[18:19] op_sel_hi:[1,0,1]
	v_pk_fma_f32 v[22:23], v[34:35], v[44:45], v[22:23] op_sel_hi:[1,0,1]
	s_waitcnt lgkmcnt(0)
	v_pk_fma_f32 v[24:25], v[38:39], v[44:45], v[24:25] op_sel_hi:[1,0,1]
	v_pk_fma_f32 v[20:21], v[40:41], v[44:45], v[20:21] op_sel_hi:[1,0,1]
	s_waitcnt vmcnt(30)
	v_lshlrev_b32_e32 v48, 16, v53
	v_pk_fma_f32 v[36:37], v[36:37], v[48:49], v[10:11] op_sel_hi:[1,0,1]
	v_pk_fma_f32 v[34:35], v[34:35], v[48:49], v[14:15] op_sel_hi:[1,0,1]
	v_pk_fma_f32 v[38:39], v[38:39], v[48:49], v[16:17] op_sel_hi:[1,0,1]
	v_pk_fma_f32 v[40:41], v[40:41], v[48:49], v[12:13] op_sel_hi:[1,0,1]
	s_waitcnt vmcnt(29)
	v_lshlrev_b32_e32 v44, 16, v54
	s_waitcnt vmcnt(28)
	v_lshlrev_b32_e32 v48, 16, v55
	ds_read_b128 v[10:13], v1 offset:2048
	ds_read_b128 v[14:17], v1 offset:2064
	s_waitcnt lgkmcnt(1)
	v_pk_fma_f32 v[22:23], v[10:11], v[44:45], v[22:23] op_sel_hi:[1,0,1]
	v_pk_fma_f32 v[34:35], v[10:11], v[48:49], v[34:35] op_sel_hi:[1,0,1]
	s_waitcnt lgkmcnt(0)
	v_pk_fma_f32 v[24:25], v[14:15], v[44:45], v[24:25] op_sel_hi:[1,0,1]
	v_pk_fma_f32 v[18:19], v[12:13], v[44:45], v[18:19] op_sel_hi:[1,0,1]
	v_pk_fma_f32 v[20:21], v[16:17], v[44:45], v[20:21] op_sel_hi:[1,0,1]
	v_pk_fma_f32 v[38:39], v[14:15], v[48:49], v[38:39] op_sel_hi:[1,0,1]
	v_pk_fma_f32 v[36:37], v[12:13], v[48:49], v[36:37] op_sel_hi:[1,0,1]
	v_pk_fma_f32 v[40:41], v[16:17], v[48:49], v[40:41] op_sel_hi:[1,0,1]
	s_waitcnt vmcnt(27)
	v_lshlrev_b32_e32 v44, 16, v56
	s_waitcnt vmcnt(26)
	v_lshlrev_b32_e32 v48, 16, v57
	ds_read_b128 v[10:13], v1 offset:4096
	ds_read_b128 v[14:17], v1 offset:4112
	s_waitcnt lgkmcnt(1)
	v_pk_fma_f32 v[22:23], v[10:11], v[44:45], v[22:23] op_sel_hi:[1,0,1]
	v_pk_fma_f32 v[50:51], v[10:11], v[48:49], v[34:35] op_sel_hi:[1,0,1]
	s_waitcnt lgkmcnt(0)
	v_pk_fma_f32 v[24:25], v[14:15], v[44:45], v[24:25] op_sel_hi:[1,0,1]
	v_pk_fma_f32 v[18:19], v[12:13], v[44:45], v[18:19] op_sel_hi:[1,0,1]
	v_pk_fma_f32 v[20:21], v[16:17], v[44:45], v[20:21] op_sel_hi:[1,0,1]
	v_pk_fma_f32 v[44:45], v[12:13], v[48:49], v[36:37] op_sel_hi:[1,0,1]
	v_pk_fma_f32 v[38:39], v[14:15], v[48:49], v[38:39] op_sel_hi:[1,0,1]
	v_pk_fma_f32 v[40:41], v[16:17], v[48:49], v[40:41] op_sel_hi:[1,0,1]
	s_waitcnt vmcnt(25)
	v_lshlrev_b32_e32 v42, 16, v58
	s_waitcnt vmcnt(24)
	v_lshlrev_b32_e32 v46, 16, v59
	ds_read_b128 v[10:13], v1 offset:6144
	ds_read_b128 v[34:37], v1 offset:6160
	s_waitcnt lgkmcnt(1)
	v_pk_fma_f32 v[22:23], v[10:11], v[42:43], v[22:23] op_sel_hi:[1,0,1]
	s_waitcnt lgkmcnt(0)
	v_pk_fma_f32 v[24:25], v[34:35], v[42:43], v[24:25] op_sel_hi:[1,0,1]
	v_pk_fma_f32 v[14:15], v[10:11], v[46:47], v[50:51] op_sel_hi:[1,0,1]
	v_pk_fma_f32 v[16:17], v[34:35], v[46:47], v[38:39] op_sel_hi:[1,0,1]
	v_pk_fma_f32 v[18:19], v[12:13], v[42:43], v[18:19] op_sel_hi:[1,0,1]
	v_pk_fma_f32 v[20:21], v[36:37], v[42:43], v[20:21] op_sel_hi:[1,0,1]
	v_pk_fma_f32 v[10:11], v[12:13], v[46:47], v[44:45] op_sel_hi:[1,0,1]
	v_pk_fma_f32 v[12:13], v[36:37], v[46:47], v[40:41] op_sel_hi:[1,0,1]
	s_waitcnt vmcnt(23)
	v_lshlrev_b32_e32 v44, 16, v60
	ds_read_b128 v[34:37], v1 offset:8192
	ds_read_b128 v[38:41], v1 offset:8208
	s_waitcnt lgkmcnt(1)
	v_pk_fma_f32 v[18:19], v[36:37], v[44:45], v[18:19] op_sel_hi:[1,0,1]
	v_pk_fma_f32 v[22:23], v[34:35], v[44:45], v[22:23] op_sel_hi:[1,0,1]
	s_waitcnt lgkmcnt(0)
	v_pk_fma_f32 v[24:25], v[38:39], v[44:45], v[24:25] op_sel_hi:[1,0,1]
	v_pk_fma_f32 v[20:21], v[40:41], v[44:45], v[20:21] op_sel_hi:[1,0,1]
	s_waitcnt vmcnt(22)
	v_lshlrev_b32_e32 v48, 16, v61
	v_pk_fma_f32 v[36:37], v[36:37], v[48:49], v[10:11] op_sel_hi:[1,0,1]
	v_pk_fma_f32 v[34:35], v[34:35], v[48:49], v[14:15] op_sel_hi:[1,0,1]
	v_pk_fma_f32 v[38:39], v[38:39], v[48:49], v[16:17] op_sel_hi:[1,0,1]
	v_pk_fma_f32 v[40:41], v[40:41], v[48:49], v[12:13] op_sel_hi:[1,0,1]
	s_waitcnt vmcnt(21)
	v_lshlrev_b32_e32 v44, 16, v62
	s_waitcnt vmcnt(20)
; #define LAS __attribute__((address_space(3)))
; DI void gates_phase(LAS unsigned char* lds, const bf16_t* X, const ss_t* ss, const float* win  , const float* ng, const float* gbias, float* GATES, int G, int bid) {
;     ...
;         for (int i = 0; i < 16; ++i) { const int k = lane + 64 * i; const float x0 = __builtin_bit_cast(float, (unsigned)xr0[k] << 16), x1 = __builtin_bit_cast(float, (unsigned)xr1[k] << 16); const f32x4 a = *(const LAS f32x4*)(wg + k * 8), b = *(const LAS f32x4*)(wg + k * 8 + 4);
; #pragma unroll
;             for (int e = 0; e < 4; ++e) { acc[0][e] += x0 * a[e]; acc[0][4 + e] += x0 * b[e]; acc[1][e] += x1 * a[e]; acc[1][4 + e] += x1 * b[e]; } }
	v_lshlrev_b32_e32 v48, 16, v63
	ds_read_b128 v[10:13], v1 offset:10240
	ds_read_b128 v[14:17], v1 offset:10256
	s_waitcnt lgkmcnt(1)
	v_pk_fma_f32 v[22:23], v[10:11], v[44:45], v[22:23] op_sel_hi:[1,0,1]
	v_pk_fma_f32 v[34:35], v[10:11], v[48:49], v[34:35] op_sel_hi:[1,0,1]
	s_waitcnt lgkmcnt(0)
	v_pk_fma_f32 v[24:25], v[14:15], v[44:45], v[24:25] op_sel_hi:[1,0,1]
	v_pk_fma_f32 v[18:19], v[12:13], v[44:45], v[18:19] op_sel_hi:[1,0,1]
	v_pk_fma_f32 v[20:21], v[16:17], v[44:45], v[20:21] op_sel_hi:[1,0,1]
	v_pk_fma_f32 v[38:39], v[14:15], v[48:49], v[38:39] op_sel_hi:[1,0,1]
	v_pk_fma_f32 v[36:37], v[12:13], v[48:49], v[36:37] op_sel_hi:[1,0,1]
	v_pk_fma_f32 v[40:41], v[16:17], v[48:49], v[40:41] op_sel_hi:[1,0,1]
	s_waitcnt vmcnt(19)
	v_lshlrev_b32_e32 v44, 16, v64
	s_waitcnt vmcnt(18)
	v_lshlrev_b32_e32 v48, 16, v65
	ds_read_b128 v[10:13], v1 offset:12288
	ds_read_b128 v[14:17], v1 offset:12304
	s_waitcnt lgkmcnt(1)
	v_pk_fma_f32 v[22:23], v[10:11], v[44:45], v[22:23] op_sel_hi:[1,0,1]
	v_pk_fma_f32 v[50:51], v[10:11], v[48:49], v[34:35] op_sel_hi:[1,0,1]
	s_waitcnt lgkmcnt(0)
	v_pk_fma_f32 v[24:25], v[14:15], v[44:45], v[24:25] op_sel_hi:[1,0,1]
	v_pk_fma_f32 v[18:19], v[12:13], v[44:45], v[18:19] op_sel_hi:[1,0,1]
	v_pk_fma_f32 v[20:21], v[16:17], v[44:45], v[20:21] op_sel_hi:[1,0,1]
	v_pk_fma_f32 v[44:45], v[12:13], v[48:49], v[36:37] op_sel_hi:[1,0,1]
	v_pk_fma_f32 v[38:39], v[14:15], v[48:49], v[38:39] op_sel_hi:[1,0,1]
	v_pk_fma_f32 v[40:41], v[16:17], v[48:49], v[40:41] op_sel_hi:[1,0,1]
	s_waitcnt vmcnt(17)
	v_lshlrev_b32_e32 v42, 16, v66
	s_waitcnt vmcnt(16)
	v_lshlrev_b32_e32 v46, 16, v67
	ds_read_b128 v[10:13], v1 offset:14336
	ds_read_b128 v[34:37], v1 offset:14352
	s_waitcnt lgkmcnt(1)
	v_pk_fma_f32 v[22:23], v[10:11], v[42:43], v[22:23] op_sel_hi:[1,0,1]
	s_waitcnt lgkmcnt(0)
	v_pk_fma_f32 v[24:25], v[34:35], v[42:43], v[24:25] op_sel_hi:[1,0,1]
	v_pk_fma_f32 v[14:15], v[10:11], v[46:47], v[50:51] op_sel_hi:[1,0,1]
	v_pk_fma_f32 v[16:17], v[34:35], v[46:47], v[38:39] op_sel_hi:[1,0,1]
	v_pk_fma_f32 v[18:19], v[12:13], v[42:43], v[18:19] op_sel_hi:[1,0,1]
	v_pk_fma_f32 v[20:21], v[36:37], v[42:43], v[20:21] op_sel_hi:[1,0,1]
	v_pk_fma_f32 v[10:11], v[12:13], v[46:47], v[44:45] op_sel_hi:[1,0,1]
	v_pk_fma_f32 v[12:13], v[36:37], v[46:47], v[40:41] op_sel_hi:[1,0,1]
	s_waitcnt vmcnt(15)
	v_lshlrev_b32_e32 v44, 16, v68
	ds_read_b128 v[34:37], v1 offset:16384
	ds_read_b128 v[38:41], v1 offset:16400
	s_waitcnt lgkmcnt(1)
	v_pk_fma_f32 v[18:19], v[36:37], v[44:45], v[18:19] op_sel_hi:[1,0,1]
	v_pk_fma_f32 v[22:23], v[34:35], v[44:45], v[22:23] op_sel_hi:[1,0,1]
	s_waitcnt lgkmcnt(0)
	v_pk_fma_f32 v[24:25], v[38:39], v[44:45], v[24:25] op_sel_hi:[1,0,1]
	v_pk_fma_f32 v[20:21], v[40:41], v[44:45], v[20:21] op_sel_hi:[1,0,1]
	s_waitcnt vmcnt(14)
	v_lshlrev_b32_e32 v48, 16, v69
	v_pk_fma_f32 v[36:37], v[36:37], v[48:49], v[10:11] op_sel_hi:[1,0,1]
	v_pk_fma_f32 v[34:35], v[34:35], v[48:49], v[14:15] op_sel_hi:[1,0,1]
	v_pk_fma_f32 v[38:39], v[38:39], v[48:49], v[16:17] op_sel_hi:[1,0,1]
	v_pk_fma_f32 v[40:41], v[40:41], v[48:49], v[12:13] op_sel_hi:[1,0,1]
	s_waitcnt vmcnt(13)
	v_lshlrev_b32_e32 v44, 16, v70
	s_waitcnt vmcnt(12)
	v_lshlrev_b32_e32 v48, 16, v71
	ds_read_b128 v[10:13], v1 offset:18432
	ds_read_b128 v[14:17], v1 offset:18448
	s_waitcnt lgkmcnt(1)
	v_pk_fma_f32 v[22:23], v[10:11], v[44:45], v[22:23] op_sel_hi:[1,0,1]
	v_pk_fma_f32 v[34:35], v[10:11], v[48:49], v[34:35] op_sel_hi:[1,0,1]
	s_waitcnt lgkmcnt(0)
	v_pk_fma_f32 v[24:25], v[14:15], v[44:45], v[24:25] op_sel_hi:[1,0,1]
	v_pk_fma_f32 v[18:19], v[12:13], v[44:45], v[18:19] op_sel_hi:[1,0,1]
	v_pk_fma_f32 v[20:21], v[16:17], v[44:45], v[20:21] op_sel_hi:[1,0,1]
	v_pk_fma_f32 v[38:39], v[14:15], v[48:49], v[38:39] op_sel_hi:[1,0,1]
	v_pk_fma_f32 v[36:37], v[12:13], v[48:49], v[36:37] op_sel_hi:[1,0,1]
	v_pk_fma_f32 v[40:41], v[16:17], v[48:49], v[40:41] op_sel_hi:[1,0,1]
	s_waitcnt vmcnt(11)
	v_lshlrev_b32_e32 v44, 16, v72
	s_waitcnt vmcnt(10)
	v_lshlrev_b32_e32 v48, 16, v73
	ds_read_b128 v[10:13], v1 offset:20480
	ds_read_b128 v[14:17], v1 offset:20496
	s_waitcnt lgkmcnt(1)
	v_pk_fma_f32 v[22:23], v[10:11], v[44:45], v[22:23] op_sel_hi:[1,0,1]
	v_pk_fma_f32 v[50:51], v[10:11], v[48:49], v[34:35] op_sel_hi:[1,0,1]
	s_waitcnt lgkmcnt(0)
	v_pk_fma_f32 v[24:25], v[14:15], v[44:45], v[24:25] op_sel_hi:[1,0,1]
	v_pk_fma_f32 v[18:19], v[12:13], v[44:45], v[18:19] op_sel_hi:[1,0,1]
	v_pk_fma_f32 v[20:21], v[16:17], v[44:45], v[20:21] op_sel_hi:[1,0,1]
	v_pk_fma_f32 v[44:45], v[12:13], v[48:49], v[36:37] op_sel_hi:[1,0,1]
	v_pk_fma_f32 v[38:39], v[14:15], v[48:49], v[38:39] op_sel_hi:[1,0,1]
	v_pk_fma_f32 v[40:41], v[16:17], v[48:49], v[40:41] op_sel_hi:[1,0,1]
	s_waitcnt vmcnt(9)
	v_lshlrev_b32_e32 v42, 16, v74
	s_waitcnt vmcnt(8)
	v_lshlrev_b32_e32 v46, 16, v75
	ds_read_b128 v[10:13], v1 offset:22528
	ds_read_b128 v[34:37], v1 offset:22544
	s_waitcnt lgkmcnt(1)
	v_pk_fma_f32 v[22:23], v[10:11], v[42:43], v[22:23] op_sel_hi:[1,0,1]
	s_waitcnt lgkmcnt(0)
	v_pk_fma_f32 v[24:25], v[34:35], v[42:43], v[24:25] op_sel_hi:[1,0,1]
	v_pk_fma_f32 v[14:15], v[10:11], v[46:47], v[50:51] op_sel_hi:[1,0,1]
	v_pk_fma_f32 v[16:17], v[34:35], v[46:47], v[38:39] op_sel_hi:[1,0,1]
	v_pk_fma_f32 v[18:19], v[12:13], v[42:43], v[18:19] op_sel_hi:[1,0,1]
	v_pk_fma_f32 v[20:21], v[36:37], v[42:43], v[20:21] op_sel_hi:[1,0,1]
	v_pk_fma_f32 v[10:11], v[12:13], v[46:47], v[44:45] op_sel_hi:[1,0,1]
	v_pk_fma_f32 v[12:13], v[36:37], v[46:47], v[40:41] op_sel_hi:[1,0,1]
	s_waitcnt vmcnt(7)
	v_lshlrev_b32_e32 v44, 16, v76
	ds_read_b128 v[34:37], v1 offset:24576
	ds_read_b128 v[38:41], v1 offset:24592
	s_waitcnt lgkmcnt(1)
; #define LAS __attribute__((address_space(3)))
; DI float frsq(float x) { return __builtin_amdgcn_rsqf(x); }
; DI float ss_get(const ss_t* ss, int r) { return (float)ss[r] * (1.0f / 1048576.0f); }
; DI void gates_phase(LAS unsigned char* lds, const bf16_t* X, const ss_t* ss, const float* win  , const float* ng, const float* gbias, float* GATES, int G, int bid) {
;     ...
;         for (int i = 0; i < 16; ++i) { const int k = lane + 64 * i; const float x0 = __builtin_bit_cast(float, (unsigned)xr0[k] << 16), x1 = __builtin_bit_cast(float, (unsigned)xr1[k] << 16); const f32x4 a = *(const LAS f32x4*)(wg + k * 8), b = *(const LAS f32x4*)(wg + k * 8 + 4);
; #pragma unroll
;             for (int e = 0; e < 4; ++e) { acc[0][e] += x0 * a[e]; acc[0][4 + e] += x0 * b[e]; acc[1][e] += x1 * a[e]; acc[1][4 + e] += x1 * b[e]; } }
; #pragma unroll
;         for (int r = 0; r < 2; ++r) {
;             float v4[4], v2[2], v1;
;             { const bool up = lane & 1;
; #pragma unroll
;               for (int e = 0; e < 4; ++e) { const float keep = up ? acc[r][4 + e] : acc[r][e], send = up ? acc[r][e] : acc[r][4 + e]; v4[e] = keep + __shfl_xor(send, 1); } }
;             { const bool up = lane & 2;
; #pragma unroll
;               for (int e = 0; e < 2; ++e) { const float keep = up ? v4[2 + e] : v4[e], send = up ? v4[e] : v4[2 + e]; v2[e] = keep + __shfl_xor(send, 2); } }
;             { const bool up = lane & 4; const float keep = up ? v2[1] : v2[0], send = up ? v2[0] : v2[1]; v1 = keep + __shfl_xor(send, 4); }
;             v1 += __shfl_xor(v1, 8); v1 += __shfl_xor(v1, 16); v1 += __shfl_xor(v1, 32);
;             const int m = m0 + r * NGW;
;             const float rs = frsq(ss_get(ss, m) * (1.0f / 1024.0f) + EPS);
;             if (lane < 8) { const int j = (lane & 1) * 4 + ((lane >> 1) & 1) * 2 + ((lane >> 2) & 1);
;                 float v = v1 * rs + gbias[j];
	v_pk_fma_f32 v[18:19], v[36:37], v[44:45], v[18:19] op_sel_hi:[1,0,1]
	v_pk_fma_f32 v[22:23], v[34:35], v[44:45], v[22:23] op_sel_hi:[1,0,1]
	s_waitcnt lgkmcnt(0)
	v_pk_fma_f32 v[24:25], v[38:39], v[44:45], v[24:25] op_sel_hi:[1,0,1]
	v_pk_fma_f32 v[20:21], v[40:41], v[44:45], v[20:21] op_sel_hi:[1,0,1]
	s_waitcnt vmcnt(6)
	v_lshlrev_b32_e32 v48, 16, v77
	v_pk_fma_f32 v[36:37], v[36:37], v[48:49], v[10:11] op_sel_hi:[1,0,1]
	v_pk_fma_f32 v[34:35], v[34:35], v[48:49], v[14:15] op_sel_hi:[1,0,1]
	v_pk_fma_f32 v[38:39], v[38:39], v[48:49], v[16:17] op_sel_hi:[1,0,1]
	v_pk_fma_f32 v[40:41], v[40:41], v[48:49], v[12:13] op_sel_hi:[1,0,1]
	s_waitcnt vmcnt(5)
	v_lshlrev_b32_e32 v44, 16, v78
	s_waitcnt vmcnt(4)
	v_lshlrev_b32_e32 v48, 16, v79
	ds_read_b128 v[10:13], v1 offset:26624
	ds_read_b128 v[14:17], v1 offset:26640
	s_waitcnt lgkmcnt(1)
	v_pk_fma_f32 v[22:23], v[10:11], v[44:45], v[22:23] op_sel_hi:[1,0,1]
	v_pk_fma_f32 v[34:35], v[10:11], v[48:49], v[34:35] op_sel_hi:[1,0,1]
	s_waitcnt lgkmcnt(0)
	v_pk_fma_f32 v[24:25], v[14:15], v[44:45], v[24:25] op_sel_hi:[1,0,1]
	v_pk_fma_f32 v[18:19], v[12:13], v[44:45], v[18:19] op_sel_hi:[1,0,1]
	v_pk_fma_f32 v[20:21], v[16:17], v[44:45], v[20:21] op_sel_hi:[1,0,1]
	v_pk_fma_f32 v[38:39], v[14:15], v[48:49], v[38:39] op_sel_hi:[1,0,1]
	v_pk_fma_f32 v[36:37], v[12:13], v[48:49], v[36:37] op_sel_hi:[1,0,1]
	v_pk_fma_f32 v[40:41], v[16:17], v[48:49], v[40:41] op_sel_hi:[1,0,1]
	s_waitcnt vmcnt(3)
	v_lshlrev_b32_e32 v44, 16, v80
	s_waitcnt vmcnt(2)
	v_lshlrev_b32_e32 v48, 16, v81
	ds_read_b128 v[10:13], v1 offset:28672
	ds_read_b128 v[14:17], v1 offset:28688
	s_waitcnt lgkmcnt(1)
	v_pk_fma_f32 v[22:23], v[10:11], v[44:45], v[22:23] op_sel_hi:[1,0,1]
	v_pk_fma_f32 v[50:51], v[10:11], v[48:49], v[34:35] op_sel_hi:[1,0,1]
	s_waitcnt lgkmcnt(0)
	v_pk_fma_f32 v[24:25], v[14:15], v[44:45], v[24:25] op_sel_hi:[1,0,1]
	v_pk_fma_f32 v[18:19], v[12:13], v[44:45], v[18:19] op_sel_hi:[1,0,1]
	v_pk_fma_f32 v[20:21], v[16:17], v[44:45], v[20:21] op_sel_hi:[1,0,1]
	v_pk_fma_f32 v[44:45], v[12:13], v[48:49], v[36:37] op_sel_hi:[1,0,1]
	v_pk_fma_f32 v[38:39], v[14:15], v[48:49], v[38:39] op_sel_hi:[1,0,1]
	v_pk_fma_f32 v[40:41], v[16:17], v[48:49], v[40:41] op_sel_hi:[1,0,1]
	s_waitcnt vmcnt(1)
	v_lshlrev_b32_e32 v42, 16, v82
	s_waitcnt vmcnt(0)
	v_lshlrev_b32_e32 v46, 16, v83
	ds_read_b128 v[10:13], v1 offset:30720
	ds_read_b128 v[34:37], v1 offset:30736
	s_waitcnt lgkmcnt(1)
	v_pk_fma_f32 v[22:23], v[10:11], v[42:43], v[22:23] op_sel_hi:[1,0,1]
	s_waitcnt lgkmcnt(0)
	v_pk_fma_f32 v[24:25], v[34:35], v[42:43], v[24:25] op_sel_hi:[1,0,1]
	v_pk_fma_f32 v[14:15], v[10:11], v[46:47], v[50:51] op_sel_hi:[1,0,1]
	v_pk_fma_f32 v[16:17], v[34:35], v[46:47], v[38:39] op_sel_hi:[1,0,1]
	v_pk_fma_f32 v[18:19], v[12:13], v[42:43], v[18:19] op_sel_hi:[1,0,1]
	v_pk_fma_f32 v[20:21], v[36:37], v[42:43], v[20:21] op_sel_hi:[1,0,1]
	v_pk_fma_f32 v[10:11], v[12:13], v[46:47], v[44:45] op_sel_hi:[1,0,1]
	v_pk_fma_f32 v[12:13], v[36:37], v[46:47], v[40:41] op_sel_hi:[1,0,1]
	v_cndmask_b32_e32 v33, v24, v22, vcc
	v_cndmask_b32_e32 v22, v22, v24, vcc
	v_cndmask_b32_e32 v24, v25, v23, vcc
	v_cndmask_b32_e32 v23, v23, v25, vcc
	ds_bpermute_b32 v23, v26, v23
	ds_bpermute_b32 v22, v26, v22
	v_ashrrev_i32_e32 v1, 31, v0
	s_waitcnt lgkmcnt(1)
	v_add_f32_e32 v23, v24, v23
	v_cndmask_b32_e32 v24, v20, v18, vcc
	v_cndmask_b32_e32 v18, v18, v20, vcc
	ds_bpermute_b32 v18, v26, v18
	v_cndmask_b32_e32 v20, v21, v19, vcc
	v_cndmask_b32_e32 v19, v19, v21, vcc
	ds_bpermute_b32 v19, v26, v19
	s_waitcnt lgkmcnt(2)
	v_add_f32_e32 v22, v33, v22
	s_waitcnt lgkmcnt(1)
	v_add_f32_e32 v18, v24, v18
	s_waitcnt lgkmcnt(0)
	v_add_f32_e32 v19, v20, v19
	v_cndmask_b32_e64 v20, v18, v22, s[38:39]
	v_cndmask_b32_e64 v18, v22, v18, s[38:39]
	ds_bpermute_b32 v18, v27, v18
	s_waitcnt lgkmcnt(0)
	v_add_f32_e32 v18, v20, v18
	v_cndmask_b32_e64 v20, v19, v23, s[38:39]
	v_cndmask_b32_e64 v19, v23, v19, s[38:39]
	ds_bpermute_b32 v19, v27, v19
	s_waitcnt lgkmcnt(0)
	v_add_f32_e32 v19, v20, v19
	v_cndmask_b32_e64 v20, v19, v18, s[40:41]
	v_cndmask_b32_e64 v18, v18, v19, s[40:41]
	ds_bpermute_b32 v18, v28, v18
	s_waitcnt lgkmcnt(0)
	v_add_f32_e32 v18, v20, v18
	ds_bpermute_b32 v19, v29, v18
	s_waitcnt lgkmcnt(0)
	v_add_f32_e32 v18, v18, v19
	ds_bpermute_b32 v19, v30, v18
	s_waitcnt lgkmcnt(0)
	v_add_f32_e32 v18, v18, v19
	ds_bpermute_b32 v19, v31, v18
	s_and_saveexec_b64 s[52:53], s[42:43]
	s_cbranch_execz .LBB0_451
	v_lshl_add_u64 v[20:21], v[0:1], 3, s[48:49]
	global_load_dwordx2 v[20:21], v[20:21], off
	s_waitcnt lgkmcnt(0)
	v_add_f32_e32 v19, v18, v19
	global_load_dword v18, v[2:3], off
	s_waitcnt vmcnt(1)
	v_xor_b32_e32 v22, v20, v21
	v_ashrrev_i32_e32 v22, 31, v22
	v_ffbh_i32_e32 v23, v21
	v_add_u32_e32 v22, 32, v22
	v_add_u32_e32 v23, -1, v23
	v_min_u32_e32 v22, v23, v22
	v_lshlrev_b64 v[20:21], v22, v[20:21]
	v_min_u32_e32 v20, 1, v20
	v_or_b32_e32 v20, v21, v20
	v_cvt_f32_i32_e32 v20, v20
	v_sub_u32_e32 v21, 32, v22
	v_ldexp_f32 v20, v20, v21
	v_mul_f32_e32 v20, 0x35800000, v20
	v_fmamk_f32 v20, v20, 0x3a800000, v229
	v_rsq_f32_e32 v20, v20
	s_waitcnt vmcnt(0)
	v_fmac_f32_e32 v18, v19, v20
	s_and_saveexec_b64 s[54:55], s[44:45]
	s_cbranch_execz .LBB0_450
; DI void gates_phase(LAS unsigned char* lds, const bf16_t* X, const ss_t* ss, const float* win  , const float* ng, const float* gbias, float* GATES, int G, int bid) {
;     ...
;                 if (j >= 4) v = fminf(v, 0.f) - log1pf(expf(-fabsf(v)));
	s_mov_b32 s0, 0xbfb8aa3b
	v_mul_f32_e64 v19, |v18|, s0
	v_rndne_f32_e32 v20, v19
	v_sub_f32_e32 v21, v19, v20
	v_fma_f32 v19, |v18|, s0, -v19
	s_mov_b32 s0, 0xb2a5705f
	v_fma_f32 v19, |v18|, s0, v19
	v_add_f32_e32 v19, v21, v19
	v_exp_f32_e32 v19, v19
	v_cvt_i32_f32_e32 v20, v20
	s_mov_b32 s0, 0x42ce8ed0
	v_cmp_ngt_f32_e64 s[0:1], |v18|, s0
	v_max_f32_e32 v21, v18, v18
	v_ldexp_f32 v19, v19, v20
	v_cndmask_b32_e64 v19, 0, v19, s[0:1]
	s_mov_b32 s0, 0xc2b17218
	v_cmp_nlt_f32_e64 s[0:1], |v18|, s0
	v_min_f32_e32 v33, 0, v21
	s_nop 0
	v_cndmask_b32_e64 v40, v236, v19, s[0:1]
	v_add_f32_e32 v20, 1.0, v40
	v_add_f32_e32 v18, -1.0, v20
	v_sub_f32_e32 v19, v18, v20
	v_add_f32_e32 v19, 1.0, v19
	v_sub_f32_e32 v18, v40, v18
	v_add_f32_e32 v21, v18, v19
	v_frexp_mant_f32_e32 v22, v20
	v_cvt_f64_f32_e32 v[18:19], v20
	s_mov_b32 s0, 0x3f2aaaab
	v_frexp_exp_i32_f64_e32 v18, v[18:19]
	v_cmp_gt_f32_e64 s[0:1], s0, v22
	s_nop 1
	v_subbrev_co_u32_e64 v34, s[0:1], 0, v18, s[0:1]
	v_sub_u32_e32 v18, 0, v34
	v_ldexp_f32 v19, v20, v18
	v_add_f32_e32 v20, -1.0, v19
	v_add_f32_e32 v22, 1.0, v19
	v_ldexp_f32 v18, v21, v18
	v_add_f32_e32 v21, 1.0, v20
	v_add_f32_e32 v23, -1.0, v22
	v_sub_f32_e32 v21, v19, v21
	v_sub_f32_e32 v19, v19, v23
	v_add_f32_e32 v21, v18, v21
	v_add_f32_e32 v18, v18, v19
	v_add_f32_e32 v35, v22, v18
	v_rcp_f32_e32 v37, v35
	v_sub_f32_e32 v19, v22, v35
	v_add_f32_e32 v36, v18, v19
	v_add_f32_e32 v19, v20, v21
	v_mul_f32_e32 v39, v19, v37
	v_sub_f32_e32 v18, v20, v19
	v_mul_f32_e32 v20, v35, v39
	v_fma_f32 v22, v39, v35, -v20
	v_fmac_f32_e32 v22, v39, v36
	v_add_f32_e32 v38, v21, v18
	v_add_f32_e32 v18, v20, v22
	v_sub_f32_e32 v21, v19, v18
	v_pk_add_f32 v[24:25], v[18:19], v[20:21] neg_lo:[0,1] neg_hi:[0,1]
	v_mov_b32_e32 v23, v18
	v_pk_add_f32 v[18:19], v[24:25], v[22:23] neg_lo:[0,1] neg_hi:[0,1]
	s_mov_b32 s0, 0x3f317218
	v_add_f32_e32 v19, v38, v19
	v_add_f32_e32 v18, v18, v19
	v_add_f32_e32 v19, v21, v18
	v_mul_f32_e32 v38, v37, v19
	v_mul_f32_e32 v20, v35, v38
	v_fma_f32 v22, v38, v35, -v20
	v_fmac_f32_e32 v22, v38, v36
	v_sub_f32_e32 v21, v21, v19
	v_add_f32_e32 v35, v18, v21
	v_add_f32_e32 v18, v20, v22
	v_sub_f32_e32 v21, v19, v18
	v_pk_add_f32 v[24:25], v[18:19], v[20:21] neg_lo:[0,1] neg_hi:[0,1]
	v_mov_b32_e32 v23, v18
	v_pk_add_f32 v[18:19], v[24:25], v[22:23] neg_lo:[0,1] neg_hi:[0,1]
	s_nop 0
	v_add_f32_e32 v19, v35, v19
	v_add_f32_e32 v18, v18, v19
	v_add_f32_e32 v19, v39, v38
	v_add_f32_e32 v18, v21, v18
	v_sub_f32_e32 v20, v19, v39
	v_mul_f32_e32 v18, v37, v18
	v_sub_f32_e32 v20, v38, v20
	v_add_f32_e32 v20, v20, v18
	v_add_f32_e32 v22, v19, v20
	v_mul_f32_e32 v23, v22, v22
	v_fmamk_f32 v18, v23, 0x3e9b6dac, v230
	v_fmaak_f32 v191, v23, v18, 0x3f2aaada
	v_cvt_f32_i32_e32 v18, v34
	v_sub_f32_e32 v19, v22, v19
	v_sub_f32_e32 v19, v20, v19
	v_ldexp_f32 v24, v19, 1
	v_mul_f32_e32 v19, v22, v23
	v_ldexp_f32 v21, v22, 1
	v_pk_mul_f32 v[22:23], v[18:19], v[190:191]
	s_nop 0
	v_fma_f32 v20, v18, s0, -v22
	v_fmac_f32_e32 v20, 0xb102e308, v18
	v_pk_add_f32 v[18:19], v[22:23], v[20:21]
	s_mov_b32 s0, 0x7f800000
	v_sub_f32_e32 v21, v19, v21
	v_sub_f32_e32 v21, v23, v21
	v_add_f32_e32 v25, v24, v21
	v_mov_b32_e32 v24, v22
	v_pk_add_f32 v[22:23], v[18:19], v[22:23] neg_lo:[0,1] neg_hi:[0,1]
	v_pk_add_f32 v[34:35], v[18:19], v[24:25]
	v_mov_b32_e32 v21, v18
	v_mov_b32_e32 v23, v35
	v_pk_add_f32 v[36:37], v[20:21], v[22:23] neg_lo:[0,1] neg_hi:[0,1]
	v_pk_add_f32 v[20:21], v[20:21], v[22:23]
	v_mov_b32_e32 v24, v25
	v_pk_add_f32 v[22:23], v[20:21], v[18:19] op_sel:[1,0] op_sel_hi:[0,1] neg_lo:[0,1] neg_hi:[0,1]
	v_pk_add_f32 v[38:39], v[34:35], v[22:23] op_sel_hi:[1,0] neg_lo:[0,1] neg_hi:[0,1]
	v_mov_b32_e32 v34, v35
	v_mov_b32_e32 v35, v21
	v_pk_mov_b32 v[22:23], v[18:19], v[22:23] op_sel:[1,0]
	v_mov_b32_e32 v25, v18
	v_pk_add_f32 v[22:23], v[34:35], v[22:23] neg_lo:[0,1] neg_hi:[0,1]
	v_mov_b32_e32 v38, v36
	v_pk_add_f32 v[18:19], v[24:25], v[22:23] neg_lo:[0,1] neg_hi:[0,1]
	v_mov_b32_e32 v37, v21
	v_pk_add_f32 v[22:23], v[38:39], v[18:19]
	v_cmp_neq_f32_e64 s[0:1], s0, v40
	v_pk_add_f32 v[24:25], v[22:23], v[22:23] op_sel:[0,1] op_sel_hi:[1,0]
	s_nop 0
	v_pk_add_f32 v[20:21], v[20:21], v[24:25] op_sel:[1,0] op_sel_hi:[0,1]
	v_mov_b32_e32 v23, v20
	v_pk_add_f32 v[34:35], v[22:23], v[36:37] neg_lo:[0,1] neg_hi:[0,1]
	v_mov_b32_e32 v19, v24
	v_sub_f32_e32 v21, v22, v34
	v_pk_add_f32 v[18:19], v[18:19], v[34:35] neg_lo:[0,1] neg_hi:[0,1]
	v_sub_f32_e32 v21, v36, v21
	v_add_f32_e32 v18, v18, v21
	v_add_f32_e32 v18, v18, v19
	v_add_f32_e32 v18, v20, v18
	v_cndmask_b32_e64 v18, v236, v18, s[0:1]
	s_mov_b32 s0, 0x33800000
	v_cmp_lt_f32_e64 s[0:1], |v40|, s0
	s_nop 1
	v_cndmask_b32_e64 v18, v18, v40, s[0:1]
	v_sub_f32_e32 v18, v33, v18
